# s5_pass2 scan: B.u packed-FMA chains of the next two steps interleaved with the recurrence of the current two, u reloaded in place (same arithmetic)
# speedup vs baseline: 1.0109x; 1.0085x over previous
; __device__ __forceinline__ bf f2bf(float f) { return (bf)(pk2(f, 0.f) & 0xFFFFu); }
; __device__ __forceinline__ void s5_pass2(const Params& p, int layer, int task, char* sm) {
;     ...
;       for (int l = 0; l < 32; l++) {
;         S5_STEP(sU + l * 16)
;         sS[l * 136 + lane] = f2bf(sr); sS[l * 136 + 64 + lane] = f2bf(si);
;       }
.LBB0_1796:
	v_add_u32_e32 v41, s9, v79
	ds_read_b128 v[104:107], v41
	ds_read_b128 v[108:111], v41 offset:16
	ds_read_b128 v[112:115], v41 offset:32
	ds_read_b128 v[116:119], v41 offset:48
	ds_read_b128 v[120:123], v41 offset:64
	ds_read_b128 v[124:127], v41 offset:80
	ds_read_b128 v[128:131], v41 offset:96
	ds_read_b128 v[132:135], v41 offset:112
	s_waitcnt lgkmcnt(0)
	v_pk_mul_f32 v[140:141], v[20:21], v[104:105] op_sel:[0,1]
	v_pk_mul_f32 v[142:143], v[20:21], v[120:121] op_sel:[0,1]
	v_pk_fma_f32 v[140:141], v[52:53], v[104:105], v[140:141] op_sel_hi:[1,0,1]
	v_pk_fma_f32 v[142:143], v[52:53], v[120:121], v[142:143] op_sel_hi:[1,0,1]
	v_pk_fma_f32 v[140:141], v[54:55], v[106:107], v[140:141] op_sel_hi:[1,0,1]
	v_pk_fma_f32 v[142:143], v[54:55], v[122:123], v[142:143] op_sel_hi:[1,0,1]
	v_pk_fma_f32 v[140:141], v[22:23], v[106:107], v[140:141] op_sel:[0,1,0]
	v_pk_fma_f32 v[142:143], v[22:23], v[122:123], v[142:143] op_sel:[0,1,0]
	ds_read_b128 v[104:107], v41 offset:128
	ds_read_b128 v[120:123], v41 offset:192
	v_pk_fma_f32 v[140:141], v[56:57], v[108:109], v[140:141] op_sel_hi:[1,0,1]
	v_pk_fma_f32 v[142:143], v[56:57], v[124:125], v[142:143] op_sel_hi:[1,0,1]
	v_pk_fma_f32 v[140:141], v[16:17], v[108:109], v[140:141] op_sel:[0,1,0]
	v_pk_fma_f32 v[142:143], v[16:17], v[124:125], v[142:143] op_sel:[0,1,0]
	v_pk_fma_f32 v[140:141], v[58:59], v[110:111], v[140:141] op_sel_hi:[1,0,1]
	v_pk_fma_f32 v[142:143], v[58:59], v[126:127], v[142:143] op_sel_hi:[1,0,1]
	v_pk_fma_f32 v[140:141], v[18:19], v[110:111], v[140:141] op_sel:[0,1,0]
	v_pk_fma_f32 v[142:143], v[18:19], v[126:127], v[142:143] op_sel:[0,1,0]
	ds_read_b128 v[108:111], v41 offset:144
	ds_read_b128 v[124:127], v41 offset:208
	v_pk_fma_f32 v[140:141], v[60:61], v[112:113], v[140:141] op_sel_hi:[1,0,1]
	v_pk_fma_f32 v[142:143], v[60:61], v[128:129], v[142:143] op_sel_hi:[1,0,1]
	v_pk_fma_f32 v[140:141], v[12:13], v[112:113], v[140:141] op_sel:[0,1,0]
	v_pk_fma_f32 v[142:143], v[12:13], v[128:129], v[142:143] op_sel:[0,1,0]
	v_pk_fma_f32 v[140:141], v[62:63], v[114:115], v[140:141] op_sel_hi:[1,0,1]
	v_pk_fma_f32 v[142:143], v[62:63], v[130:131], v[142:143] op_sel_hi:[1,0,1]
	v_pk_fma_f32 v[140:141], v[14:15], v[114:115], v[140:141] op_sel:[0,1,0]
	v_pk_fma_f32 v[142:143], v[14:15], v[130:131], v[142:143] op_sel:[0,1,0]
	ds_read_b128 v[112:115], v41 offset:160
	ds_read_b128 v[128:131], v41 offset:224
	v_pk_fma_f32 v[140:141], v[64:65], v[116:117], v[140:141] op_sel_hi:[1,0,1]
	v_pk_fma_f32 v[142:143], v[64:65], v[132:133], v[142:143] op_sel_hi:[1,0,1]
	v_pk_fma_f32 v[140:141], v[8:9], v[116:117], v[140:141] op_sel:[0,1,0]
	v_pk_fma_f32 v[142:143], v[8:9], v[132:133], v[142:143] op_sel:[0,1,0]
	v_pk_fma_f32 v[140:141], v[66:67], v[118:119], v[140:141] op_sel_hi:[1,0,1]
	v_pk_fma_f32 v[142:143], v[66:67], v[134:135], v[142:143] op_sel_hi:[1,0,1]
	v_pk_fma_f32 v[140:141], v[10:11], v[118:119], v[140:141] op_sel:[0,1,0]
	v_pk_fma_f32 v[142:143], v[10:11], v[134:135], v[142:143] op_sel:[0,1,0]
	ds_read_b128 v[116:119], v41 offset:176
	ds_read_b128 v[132:135], v41 offset:240
	s_waitcnt vmcnt(5)
.Ls5scan_0:
	v_add_u32_e32 v41, s9, v79
	v_add_u32_e32 v103, v79, v40
	s_waitcnt lgkmcnt(0)
	v_pk_mul_f32 v[136:137], v[20:21], v[104:105] op_sel:[0,1]
	v_pk_mul_f32 v[138:139], v[20:21], v[120:121] op_sel:[0,1]
	v_pk_mul_f32 v[76:77], v[74:75], v[70:71] op_sel:[0,1]
	v_pk_fma_f32 v[136:137], v[52:53], v[104:105], v[136:137] op_sel_hi:[1,0,1]
	v_pk_fma_f32 v[138:139], v[52:53], v[120:121], v[138:139] op_sel_hi:[1,0,1]
	v_pk_fma_f32 v[146:147], v[68:69], v[70:71], v[76:77] neg_lo:[0,0,1] neg_hi:[0,0,1]
	v_pk_fma_f32 v[136:137], v[54:55], v[106:107], v[136:137] op_sel_hi:[1,0,1]
	v_pk_fma_f32 v[138:139], v[54:55], v[122:123], v[138:139] op_sel_hi:[1,0,1]
	v_pk_fma_f32 v[148:149], v[68:69], v[70:71], v[76:77] op_sel_hi:[1,0,1]
	v_pk_fma_f32 v[136:137], v[22:23], v[106:107], v[136:137] op_sel:[0,1,0]
	v_pk_fma_f32 v[138:139], v[22:23], v[122:123], v[138:139] op_sel:[0,1,0]
	v_mov_b32_e32 v147, v149
	ds_read_b128 v[104:107], v41 offset:256
	ds_read_b128 v[120:123], v41 offset:320
	v_pk_fma_f32 v[136:137], v[56:57], v[108:109], v[136:137] op_sel_hi:[1,0,1]
	v_pk_fma_f32 v[138:139], v[56:57], v[124:125], v[138:139] op_sel_hi:[1,0,1]
	v_pk_add_f32 v[42:43], v[146:147], v[140:141]
	v_pk_fma_f32 v[136:137], v[16:17], v[108:109], v[136:137] op_sel:[0,1,0]
	v_pk_fma_f32 v[138:139], v[16:17], v[124:125], v[138:139] op_sel:[0,1,0]
	v_cvt_pk_bf16_f32 v150, v42, s0
	ds_write_b16 v103, v150
	v_pk_fma_f32 v[136:137], v[58:59], v[110:111], v[136:137] op_sel_hi:[1,0,1]
	v_pk_fma_f32 v[138:139], v[58:59], v[126:127], v[138:139] op_sel_hi:[1,0,1]
	v_cvt_pk_bf16_f32 v151, v43, s0
	ds_write_b16 v103, v151 offset:128
	v_pk_fma_f32 v[136:137], v[18:19], v[110:111], v[136:137] op_sel:[0,1,0]
	v_pk_fma_f32 v[138:139], v[18:19], v[126:127], v[138:139] op_sel:[0,1,0]
	v_pk_mul_f32 v[76:77], v[74:75], v[42:43] op_sel:[0,1]
	ds_read_b128 v[108:111], v41 offset:272
	ds_read_b128 v[124:127], v41 offset:336
	v_pk_fma_f32 v[136:137], v[60:61], v[112:113], v[136:137] op_sel_hi:[1,0,1]
	v_pk_fma_f32 v[138:139], v[60:61], v[128:129], v[138:139] op_sel_hi:[1,0,1]
	v_pk_fma_f32 v[146:147], v[68:69], v[42:43], v[76:77] neg_lo:[0,0,1] neg_hi:[0,0,1]
	v_pk_fma_f32 v[136:137], v[12:13], v[112:113], v[136:137] op_sel:[0,1,0]
	v_pk_fma_f32 v[138:139], v[12:13], v[128:129], v[138:139] op_sel:[0,1,0]
	v_pk_fma_f32 v[148:149], v[68:69], v[42:43], v[76:77] op_sel_hi:[1,0,1]
	v_pk_fma_f32 v[136:137], v[62:63], v[114:115], v[136:137] op_sel_hi:[1,0,1]
	v_pk_fma_f32 v[138:139], v[62:63], v[130:131], v[138:139] op_sel_hi:[1,0,1]
	v_mov_b32_e32 v147, v149
	v_pk_fma_f32 v[136:137], v[14:15], v[114:115], v[136:137] op_sel:[0,1,0]
	v_pk_fma_f32 v[138:139], v[14:15], v[130:131], v[138:139] op_sel:[0,1,0]
	v_pk_add_f32 v[70:71], v[146:147], v[142:143]
	ds_read_b128 v[112:115], v41 offset:288
	ds_read_b128 v[128:131], v41 offset:352
	v_pk_fma_f32 v[136:137], v[64:65], v[116:117], v[136:137] op_sel_hi:[1,0,1]
	v_pk_fma_f32 v[138:139], v[64:65], v[132:133], v[138:139] op_sel_hi:[1,0,1]
	v_cvt_pk_bf16_f32 v150, v70, s0
	ds_write_b16 v103, v150 offset:272
	v_pk_fma_f32 v[136:137], v[8:9], v[116:117], v[136:137] op_sel:[0,1,0]
	v_pk_fma_f32 v[138:139], v[8:9], v[132:133], v[138:139] op_sel:[0,1,0]
	v_cvt_pk_bf16_f32 v151, v71, s0
	ds_write_b16 v103, v151 offset:400
	v_pk_fma_f32 v[136:137], v[66:67], v[118:119], v[136:137] op_sel_hi:[1,0,1]
	v_pk_fma_f32 v[138:139], v[66:67], v[134:135], v[138:139] op_sel_hi:[1,0,1]
	v_pk_fma_f32 v[136:137], v[10:11], v[118:119], v[136:137] op_sel:[0,1,0]
	v_pk_fma_f32 v[138:139], v[10:11], v[134:135], v[138:139] op_sel:[0,1,0]
	ds_read_b128 v[116:119], v41 offset:304
	ds_read_b128 v[132:135], v41 offset:368
	s_addk_i32 s9, 0x80
	v_add_u32_e32 v40, 0x220, v40
	v_mov_b64_e32 v[140:141], v[136:137]
	v_mov_b64_e32 v[142:143], v[138:139]
	s_cmpk_eq_i32 s9, 0x780
	s_cbranch_scc0 .Ls5scan_0
; __device__ __forceinline__ float ozero() { float z = 0.f; asm volatile("" : "+v"(z)); return z; }
; __device__ __forceinline__ bf f2bf(float f) { return (bf)(pk2(f, 0.f) & 0xFFFFu); }
; __device__ __forceinline__ f32x4 mfma16(bf16x8 a, bf16x8 b, f32x4 c) { return __builtin_amdgcn_mfma_f32_16x16x32_bf16(a, b, c, 0, 0, 0); }
; __device__ __forceinline__ void s5_pass2(const Params& p, int layer, int task, char* sm) {
;     ...
;       for (int l = 0; l < 32; l++) {
;         S5_STEP(sU + l * 16)
;         sS[l * 136 + lane] = f2bf(sr); sS[l * 136 + 64 + lane] = f2bf(si);
;       }
;       __builtin_amdgcn_wave_barrier();
; #pragma unroll
;       for (int mb = 0; mb < 2; mb++) {
;         const float z_ = ozero(); f32x4 acc = {z_, z_, z_, z_};
; #pragma unroll
;         for (int ks = 0; ks < 4; ks++) {
;           bf16x8 af = *(const bf16x8*)(sS + (16 * mb + (lane & 15)) * 136 + ks * 32 + 8 * (lane >> 4));
;           acc = mfma16(af, cf[ks], acc);
;         }
; #pragma unroll
;         for (int r = 0; r < 4; r++) {
;           const int l = 16 * mb + 4 * (lane >> 4) + r;
;           float y = acc[r] + dsk * sU[l * 16 + (lane & 15)];
;           p.YG[(tok0 + sub * 32 + l) * 512 + g * 16 + (lane & 15)] = f2bf(geluf_(y));
	v_add_u32_e32 v103, v79, v40
	v_pk_mul_f32 v[76:77], v[74:75], v[70:71] op_sel:[0,1]
	s_nop 0
	v_pk_fma_f32 v[146:147], v[68:69], v[70:71], v[76:77] neg_lo:[0,0,1] neg_hi:[0,0,1]
	s_nop 0
	v_pk_fma_f32 v[148:149], v[68:69], v[70:71], v[76:77] op_sel_hi:[1,0,1]
	s_nop 0
	v_mov_b32_e32 v147, v149
	s_nop 0
	v_pk_add_f32 v[42:43], v[146:147], v[140:141]
	s_nop 0
	v_cvt_pk_bf16_f32 v150, v42, s0
	ds_write_b16 v103, v150
	s_nop 0
	v_cvt_pk_bf16_f32 v151, v43, s0
	ds_write_b16 v103, v151 offset:128
	s_nop 0
	v_pk_mul_f32 v[76:77], v[74:75], v[42:43] op_sel:[0,1]
	s_nop 0
	v_pk_fma_f32 v[146:147], v[68:69], v[42:43], v[76:77] neg_lo:[0,0,1] neg_hi:[0,0,1]
	s_nop 0
	v_pk_fma_f32 v[148:149], v[68:69], v[42:43], v[76:77] op_sel_hi:[1,0,1]
	s_nop 0
	v_mov_b32_e32 v147, v149
	s_nop 0
	v_pk_add_f32 v[70:71], v[146:147], v[142:143]
	s_nop 0
	v_cvt_pk_bf16_f32 v150, v70, s0
	ds_write_b16 v103, v150 offset:272
	s_nop 0
	v_cvt_pk_bf16_f32 v151, v71, s0
	ds_write_b16 v103, v151 offset:400
	s_nop 0
	s_waitcnt lgkmcnt(0)
	v_mov_b32_e32 v40, v145
	ds_read_b128 v[104:107], v100 offset:2048
	ds_read_b32 v76, v83
	v_mov_b32_e32 v41, v40
	v_mov_b32_e32 v42, v40
	v_mov_b32_e32 v43, v40
	s_lshl_b32 s9, s11, 5
	v_mov_b32_e32 v77, s5
	s_cmp_eq_u32 s8, 4
	s_waitcnt vmcnt(4) lgkmcnt(1)
	v_mfma_f32_16x16x32_bf16 v[40:43], v[104:107], v[24:27], v[40:43]
	ds_read_b128 v[104:107], v100 offset:2112
	s_waitcnt vmcnt(3) lgkmcnt(0)
	v_mfma_f32_16x16x32_bf16 v[40:43], v[104:107], v[28:31], v[40:43]
	ds_read_b128 v[104:107], v100 offset:2176
	s_waitcnt vmcnt(2) lgkmcnt(0)
	v_mfma_f32_16x16x32_bf16 v[40:43], v[104:107], v[32:35], v[40:43]
	ds_read_b128 v[104:107], v100 offset:2240
	s_waitcnt vmcnt(1) lgkmcnt(0)
	v_mfma_f32_16x16x32_bf16 v[40:43], v[104:107], v[36:39], v[40:43]
	s_waitcnt vmcnt(0)
	s_nop 6
	v_fma_f32 v40, v102, v76, v40
	v_mul_f32_e32 v76, 0x3d372713, v40
	v_mul_f32_e32 v76, v40, v76
	v_fma_f32 v76, v40, v76, v40
	v_mul_f32_e32 v76, 0x3f4c422a, v76
	v_add_f32_e32 v76, v76, v76
	v_mul_f32_e32 v76, 0x3fb8aa3b, v76
	v_exp_f32_e32 v76, v76
	v_mul_f32_e32 v40, 0.5, v40
	v_add_f32_e32 v76, 1.0, v76
	v_rcp_f32_e32 v76, v76
	s_nop 0
	v_fma_f32 v76, v76, -2.0, 1.0
	v_add_f32_e32 v76, 1.0, v76
	v_mul_f32_e32 v40, v40, v76
	v_or_b32_e32 v76, s9, v82
	v_or_b32_e32 v76, s4, v76
	v_lshlrev_b64 v[104:105], 10, v[76:77]
	v_cvt_pk_bf16_f32 v40, v40, s0
	v_lshl_add_u64 v[104:105], v[72:73], 0, v[104:105]
	global_store_short v[104:105], v40, off
	ds_read_b32 v40, v85
	s_waitcnt lgkmcnt(0)
	v_fma_f32 v40, v102, v40, v41
	v_mul_f32_e32 v41, 0x3d372713, v40
	v_mul_f32_e32 v41, v40, v41
	v_fma_f32 v41, v40, v41, v40
	v_mul_f32_e32 v41, 0x3f4c422a, v41
	v_add_f32_e32 v41, v41, v41
	v_mul_f32_e32 v41, 0x3fb8aa3b, v41
	v_exp_f32_e32 v41, v41
	v_mul_f32_e32 v40, 0.5, v40
	v_add_f32_e32 v41, 1.0, v41
	v_rcp_f32_e32 v41, v41
	s_nop 0
	v_fma_f32 v41, v41, -2.0, 1.0
	v_add_f32_e32 v41, 1.0, v41
	v_mul_f32_e32 v40, v40, v41
	v_cvt_pk_bf16_f32 v103, v40, s0
	v_or_b32_e32 v40, s9, v84
	v_or_b32_e32 v76, s4, v40
	v_lshlrev_b64 v[40:41], 10, v[76:77]
	v_lshl_add_u64 v[40:41], v[72:73], 0, v[40:41]
	global_store_short v[40:41], v103, off
	ds_read_b32 v40, v87
	s_waitcnt lgkmcnt(0)
	v_fma_f32 v40, v102, v40, v42
	v_mul_f32_e32 v41, 0x3d372713, v40
	v_mul_f32_e32 v41, v40, v41
	v_fma_f32 v41, v40, v41, v40
	v_mul_f32_e32 v41, 0x3f4c422a, v41
	v_add_f32_e32 v41, v41, v41
	v_mul_f32_e32 v41, 0x3fb8aa3b, v41
	v_exp_f32_e32 v41, v41
	v_mul_f32_e32 v40, 0.5, v40
	v_add_f32_e32 v41, 1.0, v41
	v_rcp_f32_e32 v41, v41
	s_nop 0
	v_fma_f32 v41, v41, -2.0, 1.0
	v_add_f32_e32 v41, 1.0, v41
	v_mul_f32_e32 v40, v40, v41
	v_cvt_pk_bf16_f32 v42, v40, s0
	v_or_b32_e32 v40, s9, v86
	v_or_b32_e32 v76, s4, v40
	v_lshlrev_b64 v[40:41], 10, v[76:77]
	v_lshl_add_u64 v[40:41], v[72:73], 0, v[40:41]
	global_store_short v[40:41], v42, off
	ds_read_b32 v40, v89
	s_waitcnt lgkmcnt(0)
; __device__ __forceinline__ float ozero() { float z = 0.f; asm volatile("" : "+v"(z)); return z; }
; __device__ __forceinline__ bf f2bf(float f) { return (bf)(pk2(f, 0.f) & 0xFFFFu); }
; __device__ __forceinline__ f32x4 mfma16(bf16x8 a, bf16x8 b, f32x4 c) { return __builtin_amdgcn_mfma_f32_16x16x32_bf16(a, b, c, 0, 0, 0); }
; __device__ __forceinline__ void s5_pass2(const Params& p, int layer, int task, char* sm) {
;     ...
; #pragma unroll
;       for (int mb = 0; mb < 2; mb++) {
;         const float z_ = ozero(); f32x4 acc = {z_, z_, z_, z_};
; #pragma unroll
;         for (int ks = 0; ks < 4; ks++) {
;           bf16x8 af = *(const bf16x8*)(sS + (16 * mb + (lane & 15)) * 136 + ks * 32 + 8 * (lane >> 4));
;           acc = mfma16(af, cf[ks], acc);
;         }
; #pragma unroll
;         for (int r = 0; r < 4; r++) {
;           const int l = 16 * mb + 4 * (lane >> 4) + r;
;           float y = acc[r] + dsk * sU[l * 16 + (lane & 15)];
;           p.YG[(tok0 + sub * 32 + l) * 512 + g * 16 + (lane & 15)] = f2bf(geluf_(y));
;         }
;       }
	v_fmac_f32_e32 v43, v102, v40
	v_mul_f32_e32 v40, 0x3d372713, v43
	v_mul_f32_e32 v40, v43, v40
	v_fma_f32 v40, v43, v40, v43
	v_mul_f32_e32 v40, 0x3f4c422a, v40
	v_add_f32_e32 v40, v40, v40
	v_mul_f32_e32 v40, 0x3fb8aa3b, v40
	v_exp_f32_e32 v40, v40
	v_mul_f32_e32 v41, 0.5, v43
	v_add_f32_e32 v40, 1.0, v40
	v_rcp_f32_e32 v40, v40
	s_nop 0
	v_fma_f32 v40, v40, -2.0, 1.0
	v_add_f32_e32 v40, 1.0, v40
	v_mul_f32_e32 v40, v41, v40
	v_cvt_pk_bf16_f32 v42, v40, s0
	v_or_b32_e32 v40, s9, v88
	v_or_b32_e32 v76, s4, v40
	v_lshlrev_b64 v[40:41], 10, v[76:77]
	v_lshl_add_u64 v[40:41], v[72:73], 0, v[40:41]
	global_store_short v[40:41], v42, off
	v_mov_b32_e32 v40, v145
	ds_read_b128 v[104:107], v100 offset:6400
	ds_read_b32 v76, v91
	v_mov_b32_e32 v41, v40
	v_mov_b32_e32 v42, v40
	v_mov_b32_e32 v43, v40
	s_waitcnt lgkmcnt(1)
	s_nop 0
	v_mfma_f32_16x16x32_bf16 v[40:43], v[104:107], v[24:27], v[40:43]
	ds_read_b128 v[104:107], v100 offset:6464
	s_waitcnt lgkmcnt(0)
	v_mfma_f32_16x16x32_bf16 v[40:43], v[104:107], v[28:31], v[40:43]
	ds_read_b128 v[104:107], v100 offset:6528
	s_waitcnt lgkmcnt(0)
	v_mfma_f32_16x16x32_bf16 v[40:43], v[104:107], v[32:35], v[40:43]
	ds_read_b128 v[104:107], v100 offset:6592
	s_waitcnt lgkmcnt(0)
	v_mfma_f32_16x16x32_bf16 v[40:43], v[104:107], v[36:39], v[40:43]
	s_nop 7
	v_fma_f32 v40, v102, v76, v40
	v_mul_f32_e32 v76, 0x3d372713, v40
	v_mul_f32_e32 v76, v40, v76
	v_fma_f32 v76, v40, v76, v40
	v_mul_f32_e32 v76, 0x3f4c422a, v76
	v_add_f32_e32 v76, v76, v76
	v_mul_f32_e32 v76, 0x3fb8aa3b, v76
	v_exp_f32_e32 v76, v76
	v_mul_f32_e32 v40, 0.5, v40
	v_add_f32_e32 v76, 1.0, v76
	v_rcp_f32_e32 v76, v76
	s_nop 0
	v_fma_f32 v76, v76, -2.0, 1.0
	v_add_f32_e32 v76, 1.0, v76
	v_mul_f32_e32 v40, v40, v76
	v_or_b32_e32 v76, s9, v90
	v_or_b32_e32 v76, s4, v76
	v_lshlrev_b64 v[104:105], 10, v[76:77]
	v_cvt_pk_bf16_f32 v40, v40, s0
	v_lshl_add_u64 v[104:105], v[72:73], 0, v[104:105]
	global_store_short v[104:105], v40, off
	ds_read_b32 v40, v93
	s_waitcnt lgkmcnt(0)
	v_fma_f32 v40, v102, v40, v41
	v_mul_f32_e32 v41, 0x3d372713, v40
	v_mul_f32_e32 v41, v40, v41
	v_fma_f32 v41, v40, v41, v40
	v_mul_f32_e32 v41, 0x3f4c422a, v41
	v_add_f32_e32 v41, v41, v41
	v_mul_f32_e32 v41, 0x3fb8aa3b, v41
	v_exp_f32_e32 v41, v41
	v_mul_f32_e32 v40, 0.5, v40
	v_add_f32_e32 v41, 1.0, v41
	v_rcp_f32_e32 v41, v41
	s_nop 0
	v_fma_f32 v41, v41, -2.0, 1.0
	v_add_f32_e32 v41, 1.0, v41
	v_mul_f32_e32 v40, v40, v41
	v_cvt_pk_bf16_f32 v103, v40, s0
	v_or_b32_e32 v40, s9, v92
	v_or_b32_e32 v76, s4, v40
	v_lshlrev_b64 v[40:41], 10, v[76:77]
	v_lshl_add_u64 v[40:41], v[72:73], 0, v[40:41]
	global_store_short v[40:41], v103, off
	ds_read_b32 v40, v95
	s_waitcnt lgkmcnt(0)
	v_fma_f32 v40, v102, v40, v42
	v_mul_f32_e32 v41, 0x3d372713, v40
	v_mul_f32_e32 v41, v40, v41
	v_fma_f32 v41, v40, v41, v40
	v_mul_f32_e32 v41, 0x3f4c422a, v41
	v_add_f32_e32 v41, v41, v41
	v_mul_f32_e32 v41, 0x3fb8aa3b, v41
	v_exp_f32_e32 v41, v41
	v_mul_f32_e32 v40, 0.5, v40
	v_add_f32_e32 v41, 1.0, v41
	v_rcp_f32_e32 v41, v41
	s_nop 0
	v_fma_f32 v41, v41, -2.0, 1.0
	v_add_f32_e32 v41, 1.0, v41
	v_mul_f32_e32 v40, v40, v41
	v_cvt_pk_bf16_f32 v42, v40, s0
	v_or_b32_e32 v40, s9, v94
	v_or_b32_e32 v76, s4, v40
	v_lshlrev_b64 v[40:41], 10, v[76:77]
	v_lshl_add_u64 v[40:41], v[72:73], 0, v[40:41]
	global_store_short v[40:41], v42, off
	ds_read_b32 v40, v97
	s_waitcnt lgkmcnt(0)
	v_fmac_f32_e32 v43, v102, v40
	v_mul_f32_e32 v40, 0x3d372713, v43
	v_mul_f32_e32 v40, v43, v40
	v_fma_f32 v40, v43, v40, v43
	v_mul_f32_e32 v40, 0x3f4c422a, v40
	v_add_f32_e32 v40, v40, v40
	v_mul_f32_e32 v40, 0x3fb8aa3b, v40
	v_exp_f32_e32 v40, v40
	v_mul_f32_e32 v41, 0.5, v43
	v_add_f32_e32 v40, 1.0, v40
	v_rcp_f32_e32 v40, v40
	s_nop 0
	v_fma_f32 v40, v40, -2.0, 1.0
	v_add_f32_e32 v40, 1.0, v40
	v_mul_f32_e32 v40, v41, v40
	v_cvt_pk_bf16_f32 v42, v40, s0
	v_or_b32_e32 v40, s9, v96
	v_or_b32_e32 v76, s4, v40
	v_lshlrev_b64 v[40:41], 10, v[76:77]
	v_lshl_add_u64 v[40:41], v[72:73], 0, v[40:41]
	global_store_short v[40:41], v42, off
	s_cbranch_scc1 .LBB0_1789
	s_mov_b32 s11, s8
	s_branch .LBB0_1791

; __device__ __forceinline__ bf f2bf(float f) { return (bf)(pk2(f, 0.f) & 0xFFFFu); }
; __device__ __forceinline__ void s5_pass2(const Params& p, int layer, int task, char* sm) {
;     ...
;       for (int l = 0; l < 32; l++) {
;         S5_STEP(sU + l * 16)
;         sS[l * 136 + lane] = f2bf(sr); sS[l * 136 + 64 + lane] = f2bf(si);
;       }
.Ls5scan_1:
	v_add_u32_e32 v41, s9, v79
	v_add_u32_e32 v103, v79, v40
	s_waitcnt lgkmcnt(0)
	v_pk_mul_f32 v[136:137], v[20:21], v[104:105] op_sel:[0,1]
	v_pk_mul_f32 v[138:139], v[20:21], v[120:121] op_sel:[0,1]
	v_pk_mul_f32 v[76:77], v[74:75], v[70:71] op_sel:[0,1]
	v_pk_fma_f32 v[136:137], v[52:53], v[104:105], v[136:137] op_sel_hi:[1,0,1]
	v_pk_fma_f32 v[138:139], v[52:53], v[120:121], v[138:139] op_sel_hi:[1,0,1]
	v_pk_fma_f32 v[146:147], v[68:69], v[70:71], v[76:77] neg_lo:[0,0,1] neg_hi:[0,0,1]
	v_pk_fma_f32 v[136:137], v[54:55], v[106:107], v[136:137] op_sel_hi:[1,0,1]
	v_pk_fma_f32 v[138:139], v[54:55], v[122:123], v[138:139] op_sel_hi:[1,0,1]
	v_pk_fma_f32 v[148:149], v[68:69], v[70:71], v[76:77] op_sel_hi:[1,0,1]
	v_pk_fma_f32 v[136:137], v[22:23], v[106:107], v[136:137] op_sel:[0,1,0]
	v_pk_fma_f32 v[138:139], v[22:23], v[122:123], v[138:139] op_sel:[0,1,0]
	v_mov_b32_e32 v147, v149
	ds_read_b128 v[104:107], v41 offset:256
	ds_read_b128 v[120:123], v41 offset:320
	v_pk_fma_f32 v[136:137], v[56:57], v[108:109], v[136:137] op_sel_hi:[1,0,1]
	v_pk_fma_f32 v[138:139], v[56:57], v[124:125], v[138:139] op_sel_hi:[1,0,1]
	v_pk_add_f32 v[42:43], v[146:147], v[140:141]
	v_pk_fma_f32 v[136:137], v[16:17], v[108:109], v[136:137] op_sel:[0,1,0]
	v_pk_fma_f32 v[138:139], v[16:17], v[124:125], v[138:139] op_sel:[0,1,0]
	v_cvt_pk_bf16_f32 v150, v42, s0
	ds_write_b16 v103, v150
	v_pk_fma_f32 v[136:137], v[58:59], v[110:111], v[136:137] op_sel_hi:[1,0,1]
	v_pk_fma_f32 v[138:139], v[58:59], v[126:127], v[138:139] op_sel_hi:[1,0,1]
	v_cvt_pk_bf16_f32 v151, v43, s0
	ds_write_b16 v103, v151 offset:128
	v_pk_fma_f32 v[136:137], v[18:19], v[110:111], v[136:137] op_sel:[0,1,0]
	v_pk_fma_f32 v[138:139], v[18:19], v[126:127], v[138:139] op_sel:[0,1,0]
	v_pk_mul_f32 v[76:77], v[74:75], v[42:43] op_sel:[0,1]
	ds_read_b128 v[108:111], v41 offset:272
	ds_read_b128 v[124:127], v41 offset:336
	v_pk_fma_f32 v[136:137], v[60:61], v[112:113], v[136:137] op_sel_hi:[1,0,1]
	v_pk_fma_f32 v[138:139], v[60:61], v[128:129], v[138:139] op_sel_hi:[1,0,1]
	v_pk_fma_f32 v[146:147], v[68:69], v[42:43], v[76:77] neg_lo:[0,0,1] neg_hi:[0,0,1]
	v_pk_fma_f32 v[136:137], v[12:13], v[112:113], v[136:137] op_sel:[0,1,0]
	v_pk_fma_f32 v[138:139], v[12:13], v[128:129], v[138:139] op_sel:[0,1,0]
	v_pk_fma_f32 v[148:149], v[68:69], v[42:43], v[76:77] op_sel_hi:[1,0,1]
	v_pk_fma_f32 v[136:137], v[62:63], v[114:115], v[136:137] op_sel_hi:[1,0,1]
	v_pk_fma_f32 v[138:139], v[62:63], v[130:131], v[138:139] op_sel_hi:[1,0,1]
	v_mov_b32_e32 v147, v149
	v_pk_fma_f32 v[136:137], v[14:15], v[114:115], v[136:137] op_sel:[0,1,0]
	v_pk_fma_f32 v[138:139], v[14:15], v[130:131], v[138:139] op_sel:[0,1,0]
	v_pk_add_f32 v[70:71], v[146:147], v[142:143]
	ds_read_b128 v[112:115], v41 offset:288
	ds_read_b128 v[128:131], v41 offset:352
	v_pk_fma_f32 v[136:137], v[64:65], v[116:117], v[136:137] op_sel_hi:[1,0,1]
	v_pk_fma_f32 v[138:139], v[64:65], v[132:133], v[138:139] op_sel_hi:[1,0,1]
	v_cvt_pk_bf16_f32 v150, v70, s0
	ds_write_b16 v103, v150 offset:272
	v_pk_fma_f32 v[136:137], v[8:9], v[116:117], v[136:137] op_sel:[0,1,0]
	v_pk_fma_f32 v[138:139], v[8:9], v[132:133], v[138:139] op_sel:[0,1,0]
	v_cvt_pk_bf16_f32 v151, v71, s0
	ds_write_b16 v103, v151 offset:400
	v_pk_fma_f32 v[136:137], v[66:67], v[118:119], v[136:137] op_sel_hi:[1,0,1]
	v_pk_fma_f32 v[138:139], v[66:67], v[134:135], v[138:139] op_sel_hi:[1,0,1]
	v_pk_fma_f32 v[136:137], v[10:11], v[118:119], v[136:137] op_sel:[0,1,0]
	v_pk_fma_f32 v[138:139], v[10:11], v[134:135], v[138:139] op_sel:[0,1,0]
	ds_read_b128 v[116:119], v41 offset:304
	ds_read_b128 v[132:135], v41 offset:368
	s_addk_i32 s9, 0x80
	v_add_u32_e32 v40, 0x220, v40
	v_mov_b64_e32 v[140:141], v[136:137]
	v_mov_b64_e32 v[142:143], v[138:139]
	s_cmpk_eq_i32 s9, 0x780
	s_cbranch_scc0 .Ls5scan_1
	v_add_u32_e32 v103, v79, v40
	v_pk_mul_f32 v[76:77], v[74:75], v[70:71] op_sel:[0,1]
	s_nop 0
	v_pk_fma_f32 v[146:147], v[68:69], v[70:71], v[76:77] neg_lo:[0,0,1] neg_hi:[0,0,1]
	s_nop 0
	v_pk_fma_f32 v[148:149], v[68:69], v[70:71], v[76:77] op_sel_hi:[1,0,1]
	s_nop 0
	v_mov_b32_e32 v147, v149
	s_nop 0
	v_pk_add_f32 v[42:43], v[146:147], v[140:141]
	s_nop 0
	v_cvt_pk_bf16_f32 v150, v42, s0
	ds_write_b16 v103, v150
	s_nop 0
	v_cvt_pk_bf16_f32 v151, v43, s0
	ds_write_b16 v103, v151 offset:128
	s_nop 0
	v_pk_mul_f32 v[76:77], v[74:75], v[42:43] op_sel:[0,1]
	s_nop 0
	v_pk_fma_f32 v[146:147], v[68:69], v[42:43], v[76:77] neg_lo:[0,0,1] neg_hi:[0,0,1]
	s_nop 0
	v_pk_fma_f32 v[148:149], v[68:69], v[42:43], v[76:77] op_sel_hi:[1,0,1]
	s_nop 0
	v_mov_b32_e32 v147, v149
	s_nop 0
	v_pk_add_f32 v[70:71], v[146:147], v[142:143]
	s_nop 0
	v_cvt_pk_bf16_f32 v150, v70, s0
	ds_write_b16 v103, v150 offset:272
	s_nop 0
	v_cvt_pk_bf16_f32 v151, v71, s0
	ds_write_b16 v103, v151 offset:400
	s_nop 0
	s_waitcnt lgkmcnt(0)
	v_mov_b32_e32 v40, v145
	ds_read_b128 v[104:107], v100 offset:2048
	ds_read_b32 v76, v83
	v_mov_b32_e32 v41, v40
	v_mov_b32_e32 v42, v40
	v_mov_b32_e32 v43, v40
	s_lshl_b32 s9, s12, 5
	v_mov_b32_e32 v77, s5
	s_cmp_eq_u32 s8, 4
	s_waitcnt vmcnt(4) lgkmcnt(1)
	v_mfma_f32_16x16x32_bf16 v[40:43], v[104:107], v[24:27], v[40:43]
	ds_read_b128 v[104:107], v100 offset:2112
	s_waitcnt vmcnt(3) lgkmcnt(0)
	v_mfma_f32_16x16x32_bf16 v[40:43], v[104:107], v[28:31], v[40:43]
	ds_read_b128 v[104:107], v100 offset:2176
	s_waitcnt vmcnt(2) lgkmcnt(0)
	v_mfma_f32_16x16x32_bf16 v[40:43], v[104:107], v[32:35], v[40:43]
	ds_read_b128 v[104:107], v100 offset:2240
	s_waitcnt vmcnt(1) lgkmcnt(0)
	v_mfma_f32_16x16x32_bf16 v[40:43], v[104:107], v[36:39], v[40:43]
	s_waitcnt vmcnt(0)
; __device__ __forceinline__ float ozero() { float z = 0.f; asm volatile("" : "+v"(z)); return z; }
; __device__ __forceinline__ bf f2bf(float f) { return (bf)(pk2(f, 0.f) & 0xFFFFu); }
; __device__ __forceinline__ f32x4 mfma16(bf16x8 a, bf16x8 b, f32x4 c) { return __builtin_amdgcn_mfma_f32_16x16x32_bf16(a, b, c, 0, 0, 0); }
; __device__ __forceinline__ void s5_pass2(const Params& p, int layer, int task, char* sm) {
;     ...
; #pragma unroll
;       for (int mb = 0; mb < 2; mb++) {
;         const float z_ = ozero(); f32x4 acc = {z_, z_, z_, z_};
; #pragma unroll
;         for (int ks = 0; ks < 4; ks++) {
;           bf16x8 af = *(const bf16x8*)(sS + (16 * mb + (lane & 15)) * 136 + ks * 32 + 8 * (lane >> 4));
;           acc = mfma16(af, cf[ks], acc);
;         }
; #pragma unroll
;         for (int r = 0; r < 4; r++) {
;           const int l = 16 * mb + 4 * (lane >> 4) + r;
;           float y = acc[r] + dsk * sU[l * 16 + (lane & 15)];
;           p.YG[(tok0 + sub * 32 + l) * 512 + g * 16 + (lane & 15)] = f2bf(geluf_(y));
;         }
;       }
	s_nop 6
	v_fma_f32 v40, v102, v76, v40
	v_mul_f32_e32 v76, 0x3d372713, v40
	v_mul_f32_e32 v76, v40, v76
	v_fma_f32 v76, v40, v76, v40
	v_mul_f32_e32 v76, 0x3f4c422a, v76
	v_add_f32_e32 v76, v76, v76
	v_mul_f32_e32 v76, 0x3fb8aa3b, v76
	v_exp_f32_e32 v76, v76
	v_mul_f32_e32 v40, 0.5, v40
	v_add_f32_e32 v76, 1.0, v76
	v_rcp_f32_e32 v76, v76
	s_nop 0
	v_fma_f32 v76, v76, -2.0, 1.0
	v_add_f32_e32 v76, 1.0, v76
	v_mul_f32_e32 v40, v40, v76
	v_or_b32_e32 v76, s9, v82
	v_or_b32_e32 v76, s4, v76
	v_lshlrev_b64 v[104:105], 10, v[76:77]
	v_cvt_pk_bf16_f32 v40, v40, s0
	v_lshl_add_u64 v[104:105], v[72:73], 0, v[104:105]
	global_store_short v[104:105], v40, off
	ds_read_b32 v40, v85
	s_waitcnt lgkmcnt(0)
	v_fma_f32 v40, v102, v40, v41
	v_mul_f32_e32 v41, 0x3d372713, v40
	v_mul_f32_e32 v41, v40, v41
	v_fma_f32 v41, v40, v41, v40
	v_mul_f32_e32 v41, 0x3f4c422a, v41
	v_add_f32_e32 v41, v41, v41
	v_mul_f32_e32 v41, 0x3fb8aa3b, v41
	v_exp_f32_e32 v41, v41
	v_mul_f32_e32 v40, 0.5, v40
	v_add_f32_e32 v41, 1.0, v41
	v_rcp_f32_e32 v41, v41
	s_nop 0
	v_fma_f32 v41, v41, -2.0, 1.0
	v_add_f32_e32 v41, 1.0, v41
	v_mul_f32_e32 v40, v40, v41
	v_cvt_pk_bf16_f32 v103, v40, s0
	v_or_b32_e32 v40, s9, v84
	v_or_b32_e32 v76, s4, v40
	v_lshlrev_b64 v[40:41], 10, v[76:77]
	v_lshl_add_u64 v[40:41], v[72:73], 0, v[40:41]
	global_store_short v[40:41], v103, off
	ds_read_b32 v40, v87
	s_waitcnt lgkmcnt(0)
	v_fma_f32 v40, v102, v40, v42
	v_mul_f32_e32 v41, 0x3d372713, v40
	v_mul_f32_e32 v41, v40, v41
	v_fma_f32 v41, v40, v41, v40
	v_mul_f32_e32 v41, 0x3f4c422a, v41
	v_add_f32_e32 v41, v41, v41
	v_mul_f32_e32 v41, 0x3fb8aa3b, v41
	v_exp_f32_e32 v41, v41
	v_mul_f32_e32 v40, 0.5, v40
	v_add_f32_e32 v41, 1.0, v41
	v_rcp_f32_e32 v41, v41
	s_nop 0
	v_fma_f32 v41, v41, -2.0, 1.0
	v_add_f32_e32 v41, 1.0, v41
	v_mul_f32_e32 v40, v40, v41
	v_cvt_pk_bf16_f32 v42, v40, s0
	v_or_b32_e32 v40, s9, v86
	v_or_b32_e32 v76, s4, v40
	v_lshlrev_b64 v[40:41], 10, v[76:77]
	v_lshl_add_u64 v[40:41], v[72:73], 0, v[40:41]
	global_store_short v[40:41], v42, off
	ds_read_b32 v40, v89
	s_waitcnt lgkmcnt(0)
	v_fmac_f32_e32 v43, v102, v40
	v_mul_f32_e32 v40, 0x3d372713, v43
	v_mul_f32_e32 v40, v43, v40
	v_fma_f32 v40, v43, v40, v43
	v_mul_f32_e32 v40, 0x3f4c422a, v40
	v_add_f32_e32 v40, v40, v40
	v_mul_f32_e32 v40, 0x3fb8aa3b, v40
	v_exp_f32_e32 v40, v40
	v_mul_f32_e32 v41, 0.5, v43
	v_add_f32_e32 v40, 1.0, v40
	v_rcp_f32_e32 v40, v40
	s_nop 0
	v_fma_f32 v40, v40, -2.0, 1.0
	v_add_f32_e32 v40, 1.0, v40
	v_mul_f32_e32 v40, v41, v40
	v_cvt_pk_bf16_f32 v42, v40, s0
	v_or_b32_e32 v40, s9, v88
	v_or_b32_e32 v76, s4, v40
	v_lshlrev_b64 v[40:41], 10, v[76:77]
	v_lshl_add_u64 v[40:41], v[72:73], 0, v[40:41]
	global_store_short v[40:41], v42, off
	v_mov_b32_e32 v40, v145
	ds_read_b128 v[104:107], v100 offset:6400
	ds_read_b32 v76, v91
	v_mov_b32_e32 v41, v40
	v_mov_b32_e32 v42, v40
	v_mov_b32_e32 v43, v40
	s_waitcnt lgkmcnt(1)
	s_nop 0
	v_mfma_f32_16x16x32_bf16 v[40:43], v[104:107], v[24:27], v[40:43]
	ds_read_b128 v[104:107], v100 offset:6464
	s_waitcnt lgkmcnt(0)
	v_mfma_f32_16x16x32_bf16 v[40:43], v[104:107], v[28:31], v[40:43]
	ds_read_b128 v[104:107], v100 offset:6528
	s_waitcnt lgkmcnt(0)
	v_mfma_f32_16x16x32_bf16 v[40:43], v[104:107], v[32:35], v[40:43]
	ds_read_b128 v[104:107], v100 offset:6592
	s_waitcnt lgkmcnt(0)
	v_mfma_f32_16x16x32_bf16 v[40:43], v[104:107], v[36:39], v[40:43]
	s_nop 7
	v_fma_f32 v40, v102, v76, v40
	v_mul_f32_e32 v76, 0x3d372713, v40
	v_mul_f32_e32 v76, v40, v76
	v_fma_f32 v76, v40, v76, v40
	v_mul_f32_e32 v76, 0x3f4c422a, v76
	v_add_f32_e32 v76, v76, v76
	v_mul_f32_e32 v76, 0x3fb8aa3b, v76
	v_exp_f32_e32 v76, v76
	v_mul_f32_e32 v40, 0.5, v40
	v_add_f32_e32 v76, 1.0, v76
	v_rcp_f32_e32 v76, v76
	s_nop 0
	v_fma_f32 v76, v76, -2.0, 1.0
	v_add_f32_e32 v76, 1.0, v76
	v_mul_f32_e32 v40, v40, v76
	v_or_b32_e32 v76, s9, v90
	v_or_b32_e32 v76, s4, v76
	v_lshlrev_b64 v[104:105], 10, v[76:77]
	v_cvt_pk_bf16_f32 v40, v40, s0
	v_lshl_add_u64 v[104:105], v[72:73], 0, v[104:105]
	global_store_short v[104:105], v40, off
	ds_read_b32 v40, v93
	s_waitcnt lgkmcnt(0)
	v_fma_f32 v40, v102, v40, v41
	v_mul_f32_e32 v41, 0x3d372713, v40
	v_mul_f32_e32 v41, v40, v41
	v_fma_f32 v41, v40, v41, v40
	v_mul_f32_e32 v41, 0x3f4c422a, v41
	v_add_f32_e32 v41, v41, v41
	v_mul_f32_e32 v41, 0x3fb8aa3b, v41
	v_exp_f32_e32 v41, v41
	v_mul_f32_e32 v40, 0.5, v40
	v_add_f32_e32 v41, 1.0, v41
	v_rcp_f32_e32 v41, v41
	s_nop 0
	v_fma_f32 v41, v41, -2.0, 1.0
	v_add_f32_e32 v41, 1.0, v41
	v_mul_f32_e32 v40, v40, v41
	v_cvt_pk_bf16_f32 v103, v40, s0
	v_or_b32_e32 v40, s9, v92
	v_or_b32_e32 v76, s4, v40
	v_lshlrev_b64 v[40:41], 10, v[76:77]
	v_lshl_add_u64 v[40:41], v[72:73], 0, v[40:41]
	global_store_short v[40:41], v103, off
	ds_read_b32 v40, v95
	s_waitcnt lgkmcnt(0)
	v_fma_f32 v40, v102, v40, v42
	v_mul_f32_e32 v41, 0x3d372713, v40
	v_mul_f32_e32 v41, v40, v41
	v_fma_f32 v41, v40, v41, v40
	v_mul_f32_e32 v41, 0x3f4c422a, v41
	v_add_f32_e32 v41, v41, v41
	v_mul_f32_e32 v41, 0x3fb8aa3b, v41
	v_exp_f32_e32 v41, v41
	v_mul_f32_e32 v40, 0.5, v40
	v_add_f32_e32 v41, 1.0, v41
	v_rcp_f32_e32 v41, v41
	s_nop 0
	v_fma_f32 v41, v41, -2.0, 1.0
	v_add_f32_e32 v41, 1.0, v41
	v_mul_f32_e32 v40, v40, v41
	v_cvt_pk_bf16_f32 v42, v40, s0
	v_or_b32_e32 v40, s9, v94
	v_or_b32_e32 v76, s4, v40
	v_lshlrev_b64 v[40:41], 10, v[76:77]
	v_lshl_add_u64 v[40:41], v[72:73], 0, v[40:41]
	global_store_short v[40:41], v42, off
	ds_read_b32 v40, v97
	s_waitcnt lgkmcnt(0)
	v_fmac_f32_e32 v43, v102, v40
	v_mul_f32_e32 v40, 0x3d372713, v43
	v_mul_f32_e32 v40, v43, v40
	v_fma_f32 v40, v43, v40, v43
	v_mul_f32_e32 v40, 0x3f4c422a, v40
	v_add_f32_e32 v40, v40, v40
	v_mul_f32_e32 v40, 0x3fb8aa3b, v40
	v_exp_f32_e32 v40, v40
	v_mul_f32_e32 v41, 0.5, v43
	v_add_f32_e32 v40, 1.0, v40
	v_rcp_f32_e32 v40, v40
	s_nop 0
	v_fma_f32 v40, v40, -2.0, 1.0
	v_add_f32_e32 v40, 1.0, v40
	v_mul_f32_e32 v40, v41, v40
	v_cvt_pk_bf16_f32 v42, v40, s0
	v_or_b32_e32 v40, s9, v96
	v_or_b32_e32 v76, s4, v40
	v_lshlrev_b64 v[40:41], 10, v[76:77]
	v_lshl_add_u64 v[40:41], v[72:73], 0, v[40:41]
	global_store_short v[40:41], v42, off
	s_cbranch_scc1 .LBB0_2053
	s_mov_b32 s12, s8
	s_branch .LBB0_2055
